# C6: ctx Fourier j-loop reads all three shared operand sets from LDS (proj tile double-buffered by LDS-DMA, stage-1 DFT table resident for the whole loop, stage-2 table image refilled per j) instead of
# speedup vs baseline: 1.0108x; 1.0108x over previous
.LBB0_306:
	s_andn2_b64 vcc, exec, s[2:3]
	s_cbranch_vccnz .LBB0_310
	v_lshrrev_b32_e32 v0, 1, v235
	v_readlane_b32 s0, v251, 54
	v_bfe_u32 v130, v206, 6, 2
	v_and_b32_e32 v128, 16, v0
	v_readlane_b32 s1, v251, 55
	v_lshlrev_b32_e32 v0, 4, v248
	v_mov_b32_e32 v16, 0
	v_lshl_add_u64 v[100:101], s[0:1], 0, v[128:129]
	v_lshl_or_b32 v128, v130, 14, v0
	v_lshl_add_u64 v[102:103], s[12:13], 0, v[128:129]
	s_mov_b64 s[0:1], 0x2400
	v_lshl_add_u64 v[106:107], v[102:103], 0, s[0:1]
	s_mov_b64 s[0:1], 0x2800
	v_lshl_add_u64 v[108:109], v[102:103], 0, s[0:1]
	s_mov_b64 s[0:1], 0x2c00
	v_lshl_add_u64 v[110:111], v[102:103], 0, s[0:1]
	s_mov_b64 s[0:1], 0x1000
	v_lshl_add_u64 v[112:113], v[102:103], 0, s[0:1]
	s_mov_b64 s[0:1], 0x3000
	v_lshl_add_u64 v[114:115], v[102:103], 0, s[0:1]
	s_mov_b64 s[0:1], 0x1400
	v_lshl_add_u64 v[116:117], v[102:103], 0, s[0:1]
	s_mov_b64 s[0:1], 0x3400
	v_lshl_add_u64 v[118:119], v[102:103], 0, s[0:1]
	s_mov_b64 s[0:1], 0x3800
	v_lshl_add_u64 v[122:123], v[102:103], 0, s[0:1]
	s_mov_b64 s[0:1], 0x1c00
	v_lshl_add_u64 v[124:125], v[102:103], 0, s[0:1]
	s_mov_b64 s[0:1], 0x3c00
	v_lshl_add_u64 v[126:127], v[102:103], 0, s[0:1]
	v_lshlrev_b32_e32 v0, 12, v166
	v_readlane_b32 s0, v254, 23
	v_lshl_add_u64 v[104:105], v[102:103], 0, s[20:21]
	v_lshl_add_u64 v[120:121], v[102:103], 0, s[30:31]
	v_add3_u32 v128, s0, v0, v248
	v_readlane_b32 s0, v251, 52
	v_mov_b32_e32 v17, v16
	v_mov_b32_e32 v18, v16
	v_add_u32_e32 v131, s0, v164
	s_mov_b32 s0, 0
	v_mov_b32_e32 v19, v16
	v_mov_b32_e32 v20, v16
	v_mov_b32_e32 v21, v16
	v_mov_b32_e32 v22, v16
	v_mov_b32_e32 v23, v16
	v_mov_b32_e32 v24, v16
	v_mov_b32_e32 v25, v16
	v_mov_b32_e32 v26, v16
	v_mov_b32_e32 v27, v16
	v_mov_b32_e32 v28, v16
	v_mov_b32_e32 v29, v16
	v_mov_b32_e32 v30, v16
	v_mov_b32_e32 v31, v16
	v_mov_b32_e32 v0, v16
	v_mov_b32_e32 v1, v16
	v_mov_b32_e32 v2, v16
	v_mov_b32_e32 v3, v16
	v_mov_b32_e32 v4, v16
	v_mov_b32_e32 v5, v16
	v_mov_b32_e32 v6, v16
	v_mov_b32_e32 v7, v16
	v_mov_b32_e32 v8, v16
	v_mov_b32_e32 v9, v16
	v_mov_b32_e32 v10, v16
	v_mov_b32_e32 v11, v16
	v_mov_b32_e32 v12, v16
	v_mov_b32_e32 v13, v16
	v_mov_b32_e32 v14, v16
	v_mov_b32_e32 v15, v16
	s_movk_i32 s1, 0x3800
	v_mbcnt_lo_u32_b32 v236, -1, 0
	v_mbcnt_hi_u32_b32 v236, -1, v236
	v_lshlrev_b32_e32 v236, 4, v236
	s_lshl_b32 s28, s87, 7
	s_add_u32 s26, s12, s28
	s_addc_u32 s27, s13, 0
	s_add_i32 s28, s28, 0x8000
	s_lshr_b32 s29, s87, 6
	s_and_b32 s29, s29, 3
	s_lshl_b32 s29, s29, 14
	s_add_i32 s29, s29, 0x8000
	v_add_u32_e32 v205, s29, v236
	s_add_i32 m0, s28, 0x0
	s_nop 0
	global_load_lds_dwordx4 v236, s[26:27]
	s_add_u32 s26, s26, 0x400
	s_addc_u32 s27, s27, 0
	s_add_i32 m0, s28, 0x400
	s_nop 0
	global_load_lds_dwordx4 v236, s[26:27]
	s_add_u32 s26, s26, 0x400
	s_addc_u32 s27, s27, 0
	s_add_i32 m0, s28, 0x800
	s_nop 0
	global_load_lds_dwordx4 v236, s[26:27]
	s_add_u32 s26, s26, 0x400
	s_addc_u32 s27, s27, 0
	s_add_i32 m0, s28, 0xc00
	s_nop 0
	global_load_lds_dwordx4 v236, s[26:27]
	s_add_u32 s26, s26, 0x400
	s_addc_u32 s27, s27, 0
	s_add_i32 m0, s28, 0x1000
	s_nop 0
	global_load_lds_dwordx4 v236, s[26:27]
	s_add_u32 s26, s26, 0x400
	s_addc_u32 s27, s27, 0
	s_add_i32 m0, s28, 0x1400
	s_nop 0
	global_load_lds_dwordx4 v236, s[26:27]
	s_add_u32 s26, s26, 0x400
	s_addc_u32 s27, s27, 0
	s_add_i32 m0, s28, 0x1800
	s_nop 0
	global_load_lds_dwordx4 v236, s[26:27]
	s_add_u32 s26, s26, 0x400
	s_addc_u32 s27, s27, 0
	s_add_i32 m0, s28, 0x1c00
	s_nop 0
	global_load_lds_dwordx4 v236, s[26:27]
	s_add_u32 s26, s26, 0x400
	s_addc_u32 s27, s27, 0
	v_readlane_b32 s34, v251, 0
	s_and_b32 s34, s34, 1
	s_lshl_b32 s34, s34, 17
	s_lshl_b32 s28, s87, 8
	s_add_i32 s34, s34, s28
	s_add_i32 s34, s34, 0x18000
	s_add_u32 s26, s12, s34
	s_addc_u32 s27, s13, 0
	s_lshl_b32 s29, s87, 6
	s_add_i32 s29, s29, 0x18000
	s_lshr_b32 s35, s87, 8
	s_lshl_b32 s35, s35, 14
	s_add_i32 s35, s35, 0x18000
	v_add_u32_e32 v250, s35, v236
	v_mbcnt_lo_u32_b32 v236, -1, 0
	v_mbcnt_hi_u32_b32 v236, -1, v236
	v_lshlrev_b32_e32 v236, 4, v236
	s_lshr_b32 s8, s87, 6
	s_lshr_b32 s9, s8, 2
	s_and_b32 s10, s8, 3
	s_lshl_b32 s6, s10, 6
	s_mov_b32 s7, 0
	s_lshl_b32 s9, s9, 5
	s_lshl_b32 s8, s87, 5
	v_add_u32_e32 v237, s9, v131
	v_mad_i64_i32 v[200:201], s[2:3], v237, s1, v[100:101]
	s_nop 1
	v_lshl_add_u64 v[200:201], v[200:201], 0, s[6:7]
	v_lshl_add_u64 v[202:203], v[200:201], 0, 32
	s_mov_b32 m0, s8
	s_nop 0
	global_load_lds_dwordx4 v[200:201], off
	s_add_i32 m0, s8, 0x400
	s_nop 0
	global_load_lds_dwordx4 v[202:203], off
	s_add_i32 s9, s9, 64
	s_mov_b32 s10, 0
.LBB0_308:
	v_add_u32_e32 v32, 32, v131
	s_waitcnt vmcnt(0)
	s_barrier
	s_xor_b32 s11, s10, 0x4000
	v_add_u32_e32 v237, s9, v131
	v_mad_i64_i32 v[200:201], s[2:3], v237, s1, v[100:101]
	v_add_u32_e32 v204, s10, v236
	v_lshl_add_u64 v[200:201], v[200:201], 0, s[6:7]
	s_add_i32 s5, s8, s11
	v_lshl_add_u64 v[202:203], v[200:201], 0, 32
	s_mov_b32 m0, s5
	s_nop 0
	global_load_lds_dwordx4 v[200:201], off
	s_add_i32 m0, s5, 0x400
	s_nop 0
	global_load_lds_dwordx4 v[202:203], off
	s_add_i32 m0, s29, 0x0
	s_nop 0
	global_load_lds_dwordx4 v236, s[26:27]
	s_add_u32 s26, s26, 0x400
	s_addc_u32 s27, s27, 0
	s_add_i32 m0, s29, 0x400
	s_nop 0
	global_load_lds_dwordx4 v236, s[26:27]
	s_add_u32 s26, s26, 0x400
	s_addc_u32 s27, s27, 0
	s_add_i32 m0, s29, 0x800
	s_nop 0
	global_load_lds_dwordx4 v236, s[26:27]
	s_add_u32 s26, s26, 0x400
	s_addc_u32 s27, s27, 0
	s_add_i32 m0, s29, 0xc00
	s_nop 0
	global_load_lds_dwordx4 v236, s[26:27]
	s_add_u32 s26, s26, 0x400
	s_addc_u32 s27, s27, 0
	s_mov_b32 s10, s11
	ds_read_b128 v[32:35], v205
	ds_read_b128 v[96:99], v205 offset:1024
	ds_read_b128 v[36:39], v205 offset:8192
	ds_read_b128 v[132:135], v205 offset:9216
	ds_read_b128 v[40:43], v204
	ds_read_b128 v[136:139], v204 offset:1024
	ds_read_b128 v[44:47], v204 offset:8192
	ds_read_b128 v[140:143], v204 offset:9216
	ds_read_b128 v[168:171], v205 offset:2048
	ds_read_b128 v[172:175], v205 offset:3072
	ds_read_b128 v[176:179], v205 offset:10240
	ds_read_b128 v[180:183], v205 offset:11264
	ds_read_b128 v[184:187], v204 offset:2048
	ds_read_b128 v[188:191], v204 offset:3072
	ds_read_b128 v[192:195], v204 offset:10240
	s_waitcnt lgkmcnt(7)
	ds_read_b128 v[196:199], v204 offset:11264
	v_mfma_f32_32x32x16_bf16 v[80:95], v[40:43], v[32:35], 0
	v_mfma_f32_32x32x16_bf16 v[64:79], v[40:43], v[36:39], 0
	v_mfma_f32_32x32x16_bf16 v[48:63], v[44:47], v[32:35], 0
	v_mfma_f32_32x32x16_bf16 v[32:47], v[44:47], v[36:39], 0
	v_mfma_f32_32x32x16_bf16 v[80:95], v[136:139], v[96:99], v[80:95]
	v_mfma_f32_32x32x16_bf16 v[64:79], v[136:139], v[132:135], v[64:79]
	v_mfma_f32_32x32x16_bf16 v[48:63], v[140:143], v[96:99], v[48:63]
	v_mfma_f32_32x32x16_bf16 v[32:47], v[140:143], v[132:135], v[32:47]
	ds_read_b128 v[96:99], v205 offset:4096
	ds_read_b128 v[132:135], v205 offset:12288
	ds_read_b128 v[136:139], v205 offset:5120
	ds_read_b128 v[140:143], v205 offset:13312
	ds_read_b128 v[144:147], v204 offset:4096
	ds_read_b128 v[148:151], v204 offset:5120
	ds_read_b128 v[152:155], v204 offset:12288
	s_waitcnt lgkmcnt(7)
	ds_read_b128 v[156:159], v204 offset:13312
	v_mfma_f32_32x32x16_bf16 v[80:95], v[184:187], v[168:171], v[80:95]
	v_mfma_f32_32x32x16_bf16 v[64:79], v[184:187], v[176:179], v[64:79]
	v_mfma_f32_32x32x16_bf16 v[48:63], v[192:195], v[168:171], v[48:63]
	v_mfma_f32_32x32x16_bf16 v[32:47], v[192:195], v[176:179], v[32:47]
	v_mfma_f32_32x32x16_bf16 v[80:95], v[188:191], v[172:175], v[80:95]
	v_mfma_f32_32x32x16_bf16 v[64:79], v[188:191], v[180:183], v[64:79]
	v_mfma_f32_32x32x16_bf16 v[48:63], v[196:199], v[172:175], v[48:63]
	v_mfma_f32_32x32x16_bf16 v[32:47], v[196:199], v[180:183], v[32:47]
	ds_read_b128 v[168:171], v205 offset:6144
	ds_read_b128 v[172:175], v205 offset:14336
	ds_read_b128 v[176:179], v205 offset:7168
	ds_read_b128 v[180:183], v205 offset:15360
	ds_read_b128 v[184:187], v204 offset:6144
	ds_read_b128 v[188:191], v204 offset:7168
	ds_read_b128 v[192:195], v204 offset:14336
	s_waitcnt lgkmcnt(7)
	ds_read_b128 v[196:199], v204 offset:15360
	v_mfma_f32_32x32x16_bf16 v[80:95], v[144:147], v[96:99], v[80:95]
	v_mfma_f32_32x32x16_bf16 v[64:79], v[144:147], v[132:135], v[64:79]
	v_mfma_f32_32x32x16_bf16 v[48:63], v[152:155], v[96:99], v[48:63]
	v_mfma_f32_32x32x16_bf16 v[32:47], v[152:155], v[132:135], v[32:47]
	v_mfma_f32_32x32x16_bf16 v[80:95], v[148:151], v[136:139], v[80:95]
	v_mfma_f32_32x32x16_bf16 v[64:79], v[148:151], v[140:143], v[64:79]
	v_mfma_f32_32x32x16_bf16 v[48:63], v[156:159], v[136:139], v[48:63]
	v_mfma_f32_32x32x16_bf16 v[32:47], v[156:159], v[140:143], v[32:47]
	s_waitcnt lgkmcnt(0)
	v_mfma_f32_32x32x16_bf16 v[80:95], v[184:187], v[168:171], v[80:95]
	v_mfma_f32_32x32x16_bf16 v[64:79], v[184:187], v[172:175], v[64:79]
	v_mfma_f32_32x32x16_bf16 v[48:63], v[192:195], v[168:171], v[48:63]
	v_mfma_f32_32x32x16_bf16 v[32:47], v[192:195], v[172:175], v[32:47]
	v_mfma_f32_32x32x16_bf16 v[80:95], v[188:191], v[176:179], v[80:95]
	v_mfma_f32_32x32x16_bf16 v[64:79], v[188:191], v[180:183], v[64:79]
	v_mfma_f32_32x32x16_bf16 v[48:63], v[196:199], v[176:179], v[48:63]
	v_mfma_f32_32x32x16_bf16 v[32:47], v[196:199], v[180:183], v[32:47]
	s_nop 8
	v_cvt_pk_bf16_f32 v97, v82, v83
	v_cvt_pk_bf16_f32 v82, v92, v93
	v_add_u32_e32 v92, s0, v128
	v_cvt_pk_bf16_f32 v96, v80, v81
	v_cvt_pk_bf16_f32 v98, v84, v85
	v_cvt_pk_bf16_f32 v99, v86, v87
	v_cvt_pk_bf16_f32 v80, v88, v89
	v_cvt_pk_bf16_f32 v84, v64, v65
	v_cvt_pk_bf16_f32 v85, v66, v67
	v_cvt_pk_bf16_f32 v86, v68, v69
	v_cvt_pk_bf16_f32 v87, v70, v71
	v_cvt_pk_bf16_f32 v64, v72, v73
	v_cvt_pk_bf16_f32 v66, v76, v77
	v_cvt_pk_bf16_f32 v68, v48, v49
	v_cvt_pk_bf16_f32 v69, v50, v51
	v_cvt_pk_bf16_f32 v70, v52, v53
	v_cvt_pk_bf16_f32 v71, v54, v55
	v_cvt_pk_bf16_f32 v48, v56, v57
	v_cvt_pk_bf16_f32 v50, v60, v61
	v_cvt_pk_bf16_f32 v52, v32, v33
	v_cvt_pk_bf16_f32 v53, v34, v35
	v_cvt_pk_bf16_f32 v54, v36, v37
	v_cvt_pk_bf16_f32 v32, v40, v41
	v_cvt_pk_bf16_f32 v34, v44, v45
	v_cvt_pk_bf16_f32 v81, v90, v91
	v_cvt_pk_bf16_f32 v65, v74, v75
	v_cvt_pk_bf16_f32 v67, v78, v79
	v_cvt_pk_bf16_f32 v49, v58, v59
	v_cvt_pk_bf16_f32 v51, v62, v63
	v_cvt_pk_bf16_f32 v55, v38, v39
	v_cvt_pk_bf16_f32 v33, v42, v43
	v_cvt_pk_bf16_f32 v35, v46, v47
	s_waitcnt vmcnt(0)
	s_barrier
	ds_read_b128 v[36:39], v250 offset:0
	v_cvt_pk_bf16_f32 v83, v94, v95
	ds_read_b128 v[40:43], v250 offset:4096
	ds_read_b128 v[44:47], v250 offset:1024
	ds_read_b128 v[56:59], v250 offset:5120
	ds_read_b128 v[60:63], v250 offset:2048
	ds_read_b128 v[72:75], v250 offset:6144
	ds_read_b128 v[76:79], v250 offset:3072
	ds_read_b128 v[88:91], v250 offset:7168
	ds_read_b128 v[168:171], v250 offset:8192
	ds_read_b128 v[172:175], v250 offset:12288
	ds_read_b128 v[176:179], v250 offset:9216
	ds_read_b128 v[180:183], v250 offset:13312
	ds_read_b128 v[184:187], v250 offset:10240
	ds_read_b128 v[188:191], v250 offset:14336
	ds_read_b128 v[192:195], v250 offset:11264
	s_waitcnt lgkmcnt(7)
	ds_read_b128 v[196:199], v250 offset:15360
	v_mfma_f32_32x32x16_bf16 v[16:31], v[36:39], v[96:99], v[16:31]
	v_mfma_f32_32x32x16_bf16 v[16:31], v[40:43], v[84:87], v[16:31]
	v_mfma_f32_32x32x16_bf16 v[16:31], v[44:47], v[80:83], v[16:31]
	v_mfma_f32_32x32x16_bf16 v[16:31], v[56:59], v[64:67], v[16:31]
	v_mfma_f32_32x32x16_bf16 v[16:31], v[60:63], v[68:71], v[16:31]
	v_mfma_f32_32x32x16_bf16 v[16:31], v[72:75], v[52:55], v[16:31]
	v_mfma_f32_32x32x16_bf16 v[16:31], v[76:79], v[48:51], v[16:31]
	v_mfma_f32_32x32x16_bf16 v[16:31], v[88:91], v[32:35], v[16:31]
	s_waitcnt lgkmcnt(0)
	v_mfma_f32_32x32x16_bf16 v[0:15], v[168:171], v[96:99], v[0:15]
	v_mfma_f32_32x32x16_bf16 v[0:15], v[172:175], v[84:87], v[0:15]
	v_mfma_f32_32x32x16_bf16 v[0:15], v[176:179], v[80:83], v[0:15]
	v_mfma_f32_32x32x16_bf16 v[0:15], v[180:183], v[64:67], v[0:15]
	v_mfma_f32_32x32x16_bf16 v[0:15], v[184:187], v[68:71], v[0:15]
	v_mfma_f32_32x32x16_bf16 v[0:15], v[188:191], v[52:55], v[0:15]
	v_mfma_f32_32x32x16_bf16 v[0:15], v[192:195], v[48:51], v[0:15]
	v_mfma_f32_32x32x16_bf16 v[0:15], v[196:199], v[32:35], v[0:15]
	s_addk_i32 s0, 0x100
	s_cmpk_eq_i32 s0, 0x400
	v_add_u32_e32 v131, 64, v131
	s_cbranch_scc0 .LBB0_308
	v_readlane_b32 s0, v251, 50
	v_bfe_u32 v230, v206, 6, 2
	v_lshlrev_b32_e32 v231, 2, v165
	v_add_u32_e32 v232, s0, v166
	v_readlane_b32 s0, v251, 53
	v_lshl_or_b32 v232, v232, 6, v231
	v_lshlrev_b32_e32 v230, 5, v230
	v_readlane_b32 s2, v251, 56
	v_or3_b32 v230, v230, s0, v164
	v_readlane_b32 s0, v253, 59
	v_lshlrev_b32_e32 v128, 1, v230
	v_readlane_b32 s1, v253, 60
	v_ashrrev_i32_e32 v233, 31, v232
	v_readlane_b32 s3, v251, 57
	v_lshl_add_u64 v[228:229], s[0:1], 0, v[128:129]
	s_movk_i32 s4, 0x3800
	v_lshl_add_u64 v[232:233], s[2:3], 0, v[232:233]
	v_mad_u64_u32 v[226:227], s[0:1], v232, s4, v[228:229]
	v_mad_i32_i24 v227, v233, s4, v227
	global_load_ushort v167, v[226:227], off offset:1024
	s_mov_b64 s[0:1], 0x3800
	v_lshl_add_u64 v[220:221], v[226:227], 0, s[0:1]
	global_load_ushort v168, v[220:221], off offset:1024
	s_mov_b64 s[0:1], 0x7000
	v_lshl_add_u64 v[222:223], v[226:227], 0, s[0:1]
	global_load_ushort v169, v[222:223], off offset:1024
	s_mov_b64 s[0:1], 0xa800
	v_lshl_add_u64 v[224:225], v[226:227], 0, s[0:1]
	global_load_ushort v170, v[224:225], off offset:1024
	s_mov_b64 s[0:1], 0x1c000
	v_lshl_add_u64 v[218:219], v[226:227], 0, s[0:1]
	global_load_ushort v171, v[218:219], off offset:1024
	s_mov_b64 s[0:1], 0x1f800
	v_lshl_add_u64 v[220:221], v[226:227], 0, s[0:1]
	global_load_ushort v172, v[220:221], off offset:1024
	s_mov_b64 s[0:1], 0x23000
	v_lshl_add_u64 v[222:223], v[226:227], 0, s[0:1]
	global_load_ushort v173, v[222:223], off offset:1024
	s_mov_b64 s[0:1], 0x26800
	v_lshl_add_u64 v[224:225], v[226:227], 0, s[0:1]
	global_load_ushort v174, v[224:225], off offset:1024
	s_mov_b64 s[0:1], 0x38000
	v_lshl_add_u64 v[218:219], v[226:227], 0, s[0:1]
	global_load_ushort v175, v[218:219], off offset:1024
	s_mov_b64 s[0:1], 0x3b800
	v_lshl_add_u64 v[220:221], v[226:227], 0, s[0:1]
	global_load_ushort v176, v[220:221], off offset:1024
	s_mov_b64 s[0:1], 0x3f000
	v_lshl_add_u64 v[222:223], v[226:227], 0, s[0:1]
	global_load_ushort v177, v[222:223], off offset:1024
	s_mov_b64 s[0:1], 0x42800
	v_lshl_add_u64 v[224:225], v[226:227], 0, s[0:1]
	global_load_ushort v178, v[224:225], off offset:1024
	s_mov_b64 s[0:1], 0x54000
	v_lshl_add_u64 v[218:219], v[226:227], 0, s[0:1]
	global_load_ushort v179, v[218:219], off offset:1024
	s_mov_b64 s[0:1], 0x57800
	v_lshl_add_u64 v[220:221], v[226:227], 0, s[0:1]
	global_load_ushort v180, v[220:221], off offset:1024
	s_mov_b64 s[0:1], 0x5b000
	v_lshl_add_u64 v[222:223], v[226:227], 0, s[0:1]
	global_load_ushort v181, v[222:223], off offset:1024
	s_mov_b64 s[0:1], 0x5e800
	v_lshl_add_u64 v[224:225], v[226:227], 0, s[0:1]
	global_load_ushort v182, v[224:225], off offset:1024
	s_mov_b64 s[0:1], 0x70000
	v_lshl_add_u64 v[218:219], v[226:227], 0, s[0:1]
	global_load_ushort v183, v[218:219], off offset:1024
	s_mov_b64 s[0:1], 0x73800
	v_lshl_add_u64 v[220:221], v[226:227], 0, s[0:1]
	global_load_ushort v184, v[220:221], off offset:1024
	s_mov_b64 s[0:1], 0x77000
	v_lshl_add_u64 v[222:223], v[226:227], 0, s[0:1]
	global_load_ushort v185, v[222:223], off offset:1024
	s_mov_b64 s[0:1], 0x7a800
	v_lshl_add_u64 v[224:225], v[226:227], 0, s[0:1]
	global_load_ushort v186, v[224:225], off offset:1024
	s_mov_b64 s[0:1], 0x8c000
	v_lshl_add_u64 v[218:219], v[226:227], 0, s[0:1]
	global_load_ushort v187, v[218:219], off offset:1024
	s_mov_b64 s[0:1], 0x8f800
	v_lshl_add_u64 v[220:221], v[226:227], 0, s[0:1]
	global_load_ushort v188, v[220:221], off offset:1024
	s_mov_b64 s[0:1], 0x93000
	v_lshl_add_u64 v[222:223], v[226:227], 0, s[0:1]
	global_load_ushort v189, v[222:223], off offset:1024
	s_mov_b64 s[0:1], 0x96800
	v_lshl_add_u64 v[224:225], v[226:227], 0, s[0:1]
	global_load_ushort v190, v[224:225], off offset:1024
	s_mov_b64 s[0:1], 0xa8000
	v_lshl_add_u64 v[218:219], v[226:227], 0, s[0:1]
	global_load_ushort v191, v[218:219], off offset:1024
	s_mov_b64 s[0:1], 0xab800
	v_lshl_add_u64 v[220:221], v[226:227], 0, s[0:1]
	global_load_ushort v192, v[220:221], off offset:1024
	s_mov_b64 s[0:1], 0xaf000
	v_lshl_add_u64 v[222:223], v[226:227], 0, s[0:1]
	global_load_ushort v193, v[222:223], off offset:1024
	s_mov_b64 s[0:1], 0xb2800
	v_lshl_add_u64 v[224:225], v[226:227], 0, s[0:1]
	global_load_ushort v194, v[224:225], off offset:1024
	s_mov_b64 s[0:1], 0xc4000
	v_lshl_add_u64 v[218:219], v[226:227], 0, s[0:1]
	global_load_ushort v195, v[218:219], off offset:1024
	s_mov_b64 s[0:1], 0xc7800
	v_lshl_add_u64 v[220:221], v[226:227], 0, s[0:1]
	global_load_ushort v196, v[220:221], off offset:1024
	s_mov_b64 s[0:1], 0xcb000
	v_lshl_add_u64 v[222:223], v[226:227], 0, s[0:1]
	global_load_ushort v197, v[222:223], off offset:1024
	s_mov_b64 s[0:1], 0xce800
	v_lshl_add_u64 v[224:225], v[226:227], 0, s[0:1]
	global_load_ushort v198, v[224:225], off offset:1024
	v_readlane_b32 s0, v251, 25
	v_readlane_b32 s1, v251, 26
	v_lshlrev_b32_e32 v128, 1, v230
	v_lshlrev_b64 v[224:225], 10, v[232:233]
	v_lshl_add_u64 v[228:229], s[0:1], 0, v[128:129]
	v_lshl_add_u64 v[228:229], v[228:229], 0, v[224:225]
	s_waitcnt vmcnt(0)
	v_lshlrev_b32_e32 v167, 16, v167
	v_mul_f32_e32 v207, 0xbfb8aa3b, v167
	v_exp_f32_e32 v207, v207
	v_lshlrev_b32_e32 v168, 16, v168
	v_mul_f32_e32 v208, 0xbfb8aa3b, v168
	v_exp_f32_e32 v208, v208
	v_lshlrev_b32_e32 v169, 16, v169
	v_mul_f32_e32 v209, 0xbfb8aa3b, v169
	v_exp_f32_e32 v209, v209
	v_lshlrev_b32_e32 v170, 16, v170
	v_mul_f32_e32 v210, 0xbfb8aa3b, v170
	v_exp_f32_e32 v210, v210
	v_lshlrev_b32_e32 v171, 16, v171
	v_mul_f32_e32 v211, 0xbfb8aa3b, v171
	v_exp_f32_e32 v211, v211
	v_lshlrev_b32_e32 v172, 16, v172
	v_mul_f32_e32 v212, 0xbfb8aa3b, v172
	v_exp_f32_e32 v212, v212
	v_lshlrev_b32_e32 v173, 16, v173
	v_mul_f32_e32 v213, 0xbfb8aa3b, v173
	v_exp_f32_e32 v213, v213
	v_lshlrev_b32_e32 v174, 16, v174
	v_mul_f32_e32 v214, 0xbfb8aa3b, v174
	v_exp_f32_e32 v214, v214
	v_lshlrev_b32_e32 v175, 16, v175
	v_mul_f32_e32 v215, 0xbfb8aa3b, v175
	v_exp_f32_e32 v215, v215
	v_lshlrev_b32_e32 v176, 16, v176
	v_mul_f32_e32 v216, 0xbfb8aa3b, v176
	v_exp_f32_e32 v216, v216
	v_lshlrev_b32_e32 v177, 16, v177
	v_mul_f32_e32 v217, 0xbfb8aa3b, v177
	v_exp_f32_e32 v217, v217
	v_lshlrev_b32_e32 v178, 16, v178
	v_mul_f32_e32 v218, 0xbfb8aa3b, v178
	v_exp_f32_e32 v218, v218
	v_lshlrev_b32_e32 v179, 16, v179
	v_mul_f32_e32 v219, 0xbfb8aa3b, v179
	v_exp_f32_e32 v219, v219
	v_lshlrev_b32_e32 v180, 16, v180
	v_mul_f32_e32 v220, 0xbfb8aa3b, v180
	v_exp_f32_e32 v220, v220
	v_lshlrev_b32_e32 v181, 16, v181
	v_mul_f32_e32 v221, 0xbfb8aa3b, v181
	v_exp_f32_e32 v221, v221
	v_lshlrev_b32_e32 v182, 16, v182
	v_mul_f32_e32 v222, 0xbfb8aa3b, v182
	v_exp_f32_e32 v222, v222
	s_nop 0
	v_add_f32_e32 v207, 1.0, v207
	v_add_f32_e32 v208, 1.0, v208
	v_add_f32_e32 v209, 1.0, v209
	v_add_f32_e32 v210, 1.0, v210
	v_add_f32_e32 v211, 1.0, v211
	v_add_f32_e32 v212, 1.0, v212
	v_add_f32_e32 v213, 1.0, v213
	v_add_f32_e32 v214, 1.0, v214
	v_add_f32_e32 v215, 1.0, v215
	v_add_f32_e32 v216, 1.0, v216
	v_add_f32_e32 v217, 1.0, v217
	v_add_f32_e32 v218, 1.0, v218
	v_add_f32_e32 v219, 1.0, v219
	v_add_f32_e32 v220, 1.0, v220
	v_add_f32_e32 v221, 1.0, v221
	v_add_f32_e32 v222, 1.0, v222
	v_rcp_f32_e32 v207, v207
	v_rcp_f32_e32 v208, v208
	v_rcp_f32_e32 v209, v209
	v_rcp_f32_e32 v210, v210
	v_rcp_f32_e32 v211, v211
	v_rcp_f32_e32 v212, v212
	v_rcp_f32_e32 v213, v213
	v_rcp_f32_e32 v214, v214
	v_rcp_f32_e32 v215, v215
	v_rcp_f32_e32 v216, v216
	v_rcp_f32_e32 v217, v217
	v_rcp_f32_e32 v218, v218
	v_rcp_f32_e32 v219, v219
	v_rcp_f32_e32 v220, v220
	v_rcp_f32_e32 v221, v221
	v_rcp_f32_e32 v222, v222
	s_nop 0
	v_mul_f32_e32 v167, v207, v167
	v_mul_f32_e32 v168, v208, v168
	v_mul_f32_e32 v169, v209, v169
	v_mul_f32_e32 v170, v210, v170
	v_mul_f32_e32 v171, v211, v171
	v_mul_f32_e32 v172, v212, v172
	v_mul_f32_e32 v173, v213, v173
	v_mul_f32_e32 v174, v214, v174
	v_mul_f32_e32 v175, v215, v175
	v_mul_f32_e32 v176, v216, v176
	v_mul_f32_e32 v177, v217, v177
	v_mul_f32_e32 v178, v218, v178
	v_mul_f32_e32 v179, v219, v179
	v_mul_f32_e32 v180, v220, v180
	v_mul_f32_e32 v181, v221, v181
	v_mul_f32_e32 v182, v222, v182
	v_lshlrev_b32_e32 v183, 16, v183
	v_mul_f32_e32 v207, 0xbfb8aa3b, v183
	v_exp_f32_e32 v207, v207
	v_lshlrev_b32_e32 v184, 16, v184
	v_mul_f32_e32 v208, 0xbfb8aa3b, v184
	v_exp_f32_e32 v208, v208
	v_lshlrev_b32_e32 v185, 16, v185
	v_mul_f32_e32 v209, 0xbfb8aa3b, v185
	v_exp_f32_e32 v209, v209
	v_lshlrev_b32_e32 v186, 16, v186
	v_mul_f32_e32 v210, 0xbfb8aa3b, v186
	v_exp_f32_e32 v210, v210
	v_lshlrev_b32_e32 v187, 16, v187
	v_mul_f32_e32 v211, 0xbfb8aa3b, v187
	v_exp_f32_e32 v211, v211
	v_lshlrev_b32_e32 v188, 16, v188
	v_mul_f32_e32 v212, 0xbfb8aa3b, v188
	v_exp_f32_e32 v212, v212
	v_lshlrev_b32_e32 v189, 16, v189
	v_mul_f32_e32 v213, 0xbfb8aa3b, v189
	v_exp_f32_e32 v213, v213
	v_lshlrev_b32_e32 v190, 16, v190
	v_mul_f32_e32 v214, 0xbfb8aa3b, v190
	v_exp_f32_e32 v214, v214
	v_lshlrev_b32_e32 v191, 16, v191
	v_mul_f32_e32 v215, 0xbfb8aa3b, v191
	v_exp_f32_e32 v215, v215
	v_lshlrev_b32_e32 v192, 16, v192
	v_mul_f32_e32 v216, 0xbfb8aa3b, v192
	v_exp_f32_e32 v216, v216
	v_lshlrev_b32_e32 v193, 16, v193
	v_mul_f32_e32 v217, 0xbfb8aa3b, v193
	v_exp_f32_e32 v217, v217
	v_lshlrev_b32_e32 v194, 16, v194
	v_mul_f32_e32 v218, 0xbfb8aa3b, v194
	v_exp_f32_e32 v218, v218
	v_lshlrev_b32_e32 v195, 16, v195
	v_mul_f32_e32 v219, 0xbfb8aa3b, v195
	v_exp_f32_e32 v219, v219
	v_lshlrev_b32_e32 v196, 16, v196
	v_mul_f32_e32 v220, 0xbfb8aa3b, v196
	v_exp_f32_e32 v220, v220
	v_lshlrev_b32_e32 v197, 16, v197
	v_mul_f32_e32 v221, 0xbfb8aa3b, v197
	v_exp_f32_e32 v221, v221
	v_lshlrev_b32_e32 v198, 16, v198
	v_mul_f32_e32 v222, 0xbfb8aa3b, v198
	v_exp_f32_e32 v222, v222
	s_nop 0
	v_add_f32_e32 v207, 1.0, v207
	v_add_f32_e32 v208, 1.0, v208
	v_add_f32_e32 v209, 1.0, v209
	v_add_f32_e32 v210, 1.0, v210
	v_add_f32_e32 v211, 1.0, v211
	v_add_f32_e32 v212, 1.0, v212
	v_add_f32_e32 v213, 1.0, v213
	v_add_f32_e32 v214, 1.0, v214
	v_add_f32_e32 v215, 1.0, v215
	v_add_f32_e32 v216, 1.0, v216
	v_add_f32_e32 v217, 1.0, v217
	v_add_f32_e32 v218, 1.0, v218
	v_add_f32_e32 v219, 1.0, v219
	v_add_f32_e32 v220, 1.0, v220
	v_add_f32_e32 v221, 1.0, v221
	v_add_f32_e32 v222, 1.0, v222
	v_rcp_f32_e32 v207, v207
	v_rcp_f32_e32 v208, v208
	v_rcp_f32_e32 v209, v209
	v_rcp_f32_e32 v210, v210
	v_rcp_f32_e32 v211, v211
	v_rcp_f32_e32 v212, v212
	v_rcp_f32_e32 v213, v213
	v_rcp_f32_e32 v214, v214
	v_rcp_f32_e32 v215, v215
	v_rcp_f32_e32 v216, v216
	v_rcp_f32_e32 v217, v217
	v_rcp_f32_e32 v218, v218
	v_rcp_f32_e32 v219, v219
	v_rcp_f32_e32 v220, v220
	v_rcp_f32_e32 v221, v221
	v_rcp_f32_e32 v222, v222
	s_nop 0
	v_mul_f32_e32 v183, v207, v183
	v_mul_f32_e32 v184, v208, v184
	v_mul_f32_e32 v185, v209, v185
	v_mul_f32_e32 v186, v210, v186
	v_mul_f32_e32 v187, v211, v187
	v_mul_f32_e32 v188, v212, v188
	v_mul_f32_e32 v189, v213, v189
	v_mul_f32_e32 v190, v214, v190
	v_mul_f32_e32 v191, v215, v191
	v_mul_f32_e32 v192, v216, v192
	v_mul_f32_e32 v193, v217, v193
	v_mul_f32_e32 v194, v218, v194
	v_mul_f32_e32 v195, v219, v195
	v_mul_f32_e32 v196, v220, v196
	v_mul_f32_e32 v197, v221, v197
	v_mul_f32_e32 v198, v222, v198
	v_mul_f32_e32 v16, 0x3bb504f3, v16
	v_mul_f32_e32 v17, 0x3bb504f3, v17
	v_mul_f32_e32 v18, 0x3bb504f3, v18
	v_mul_f32_e32 v19, 0x3bb504f3, v19
	v_mul_f32_e32 v20, 0x3bb504f3, v20
	v_mul_f32_e32 v21, 0x3bb504f3, v21
	v_mul_f32_e32 v22, 0x3bb504f3, v22
	v_mul_f32_e32 v23, 0x3bb504f3, v23
	v_mul_f32_e32 v24, 0x3bb504f3, v24
	v_mul_f32_e32 v25, 0x3bb504f3, v25
	v_mul_f32_e32 v26, 0x3bb504f3, v26
	v_mul_f32_e32 v27, 0x3bb504f3, v27
	v_mul_f32_e32 v28, 0x3bb504f3, v28
	v_mul_f32_e32 v29, 0x3bb504f3, v29
	v_mul_f32_e32 v30, 0x3bb504f3, v30
	v_mul_f32_e32 v31, 0x3bb504f3, v31
	v_mul_f32_e32 v0, 0x3bb504f3, v0
	v_mul_f32_e32 v1, 0x3bb504f3, v1
	v_mul_f32_e32 v2, 0x3bb504f3, v2
	v_mul_f32_e32 v3, 0x3bb504f3, v3
	v_mul_f32_e32 v4, 0x3bb504f3, v4
	v_mul_f32_e32 v5, 0x3bb504f3, v5
	v_mul_f32_e32 v6, 0x3bb504f3, v6
	v_mul_f32_e32 v7, 0x3bb504f3, v7
	v_mul_f32_e32 v8, 0x3bb504f3, v8
	v_mul_f32_e32 v9, 0x3bb504f3, v9
	v_mul_f32_e32 v10, 0x3bb504f3, v10
	v_mul_f32_e32 v11, 0x3bb504f3, v11
	v_mul_f32_e32 v12, 0x3bb504f3, v12
	v_mul_f32_e32 v13, 0x3bb504f3, v13
	v_mul_f32_e32 v14, 0x3bb504f3, v14
	v_mul_f32_e32 v15, 0x3bb504f3, v15
	v_mul_f32_e32 v16, v16, v167
	v_mul_f32_e32 v17, v17, v168
	v_mul_f32_e32 v18, v18, v169
	v_mul_f32_e32 v19, v19, v170
	v_mul_f32_e32 v20, v20, v171
	v_mul_f32_e32 v21, v21, v172
	v_mul_f32_e32 v22, v22, v173
	v_mul_f32_e32 v23, v23, v174
	v_mul_f32_e32 v24, v24, v175
	v_mul_f32_e32 v25, v25, v176
	v_mul_f32_e32 v26, v26, v177
	v_mul_f32_e32 v27, v27, v178
	v_mul_f32_e32 v28, v28, v179
	v_mul_f32_e32 v29, v29, v180
	v_mul_f32_e32 v30, v30, v181
	v_mul_f32_e32 v31, v31, v182
	v_mul_f32_e32 v0, v0, v183
	v_mul_f32_e32 v1, v1, v184
	v_mul_f32_e32 v2, v2, v185
	v_mul_f32_e32 v3, v3, v186
	v_mul_f32_e32 v4, v4, v187
	v_mul_f32_e32 v5, v5, v188
	v_mul_f32_e32 v6, v6, v189
	v_mul_f32_e32 v7, v7, v190
	v_mul_f32_e32 v8, v8, v191
	v_mul_f32_e32 v9, v9, v192
	v_mul_f32_e32 v10, v10, v193
	v_mul_f32_e32 v11, v11, v194
	v_mul_f32_e32 v12, v12, v195
	v_mul_f32_e32 v13, v13, v196
	v_mul_f32_e32 v14, v14, v197
	v_mul_f32_e32 v15, v15, v198
	v_cvt_pk_bf16_f32 v207, v16, v17
	v_mov_b64_e32 v[216:217], v[228:229]
	global_store_short v[216:217], v207, off
	global_store_short_d16_hi v[216:217], v207, off offset:1024
	v_cvt_pk_bf16_f32 v208, v18, v19
	s_mov_b64 s[0:1], 0x800
	v_lshl_add_u64 v[218:219], v[228:229], 0, s[0:1]
	global_store_short v[218:219], v208, off
	global_store_short_d16_hi v[218:219], v208, off offset:1024
	v_cvt_pk_bf16_f32 v209, v20, v21
	s_mov_b64 s[0:1], 0x2000
	v_lshl_add_u64 v[220:221], v[228:229], 0, s[0:1]
	global_store_short v[220:221], v209, off
	global_store_short_d16_hi v[220:221], v209, off offset:1024
	v_cvt_pk_bf16_f32 v210, v22, v23
	s_mov_b64 s[0:1], 0x2800
	v_lshl_add_u64 v[222:223], v[228:229], 0, s[0:1]
	global_store_short v[222:223], v210, off
	global_store_short_d16_hi v[222:223], v210, off offset:1024
	v_cvt_pk_bf16_f32 v211, v24, v25
	s_mov_b64 s[0:1], 0x4000
	v_lshl_add_u64 v[216:217], v[228:229], 0, s[0:1]
	global_store_short v[216:217], v211, off
	global_store_short_d16_hi v[216:217], v211, off offset:1024
	v_cvt_pk_bf16_f32 v212, v26, v27
	s_mov_b64 s[0:1], 0x4800
	v_lshl_add_u64 v[218:219], v[228:229], 0, s[0:1]
	global_store_short v[218:219], v212, off
	global_store_short_d16_hi v[218:219], v212, off offset:1024
	v_cvt_pk_bf16_f32 v213, v28, v29
	s_mov_b64 s[0:1], 0x6000
	v_lshl_add_u64 v[220:221], v[228:229], 0, s[0:1]
	global_store_short v[220:221], v213, off
	global_store_short_d16_hi v[220:221], v213, off offset:1024
	v_cvt_pk_bf16_f32 v214, v30, v31
	s_mov_b64 s[0:1], 0x6800
	v_lshl_add_u64 v[222:223], v[228:229], 0, s[0:1]
	global_store_short v[222:223], v214, off
	global_store_short_d16_hi v[222:223], v214, off offset:1024
	v_cvt_pk_bf16_f32 v207, v0, v1
	s_mov_b64 s[0:1], 0x8000
	v_lshl_add_u64 v[216:217], v[228:229], 0, s[0:1]
	global_store_short v[216:217], v207, off
	global_store_short_d16_hi v[216:217], v207, off offset:1024
	v_cvt_pk_bf16_f32 v208, v2, v3
	s_mov_b64 s[0:1], 0x8800
	v_lshl_add_u64 v[218:219], v[228:229], 0, s[0:1]
	global_store_short v[218:219], v208, off
	global_store_short_d16_hi v[218:219], v208, off offset:1024
	v_cvt_pk_bf16_f32 v209, v4, v5
	s_mov_b64 s[0:1], 0xa000
	v_lshl_add_u64 v[220:221], v[228:229], 0, s[0:1]
	global_store_short v[220:221], v209, off
	global_store_short_d16_hi v[220:221], v209, off offset:1024
	v_cvt_pk_bf16_f32 v210, v6, v7
	s_mov_b64 s[0:1], 0xa800
	v_lshl_add_u64 v[222:223], v[228:229], 0, s[0:1]
	global_store_short v[222:223], v210, off
	global_store_short_d16_hi v[222:223], v210, off offset:1024
	v_cvt_pk_bf16_f32 v211, v8, v9
	s_mov_b64 s[0:1], 0xc000
	v_lshl_add_u64 v[216:217], v[228:229], 0, s[0:1]
	global_store_short v[216:217], v211, off
	global_store_short_d16_hi v[216:217], v211, off offset:1024
	v_cvt_pk_bf16_f32 v212, v10, v11
	s_mov_b64 s[0:1], 0xc800
	v_lshl_add_u64 v[218:219], v[228:229], 0, s[0:1]
	global_store_short v[218:219], v212, off
	global_store_short_d16_hi v[218:219], v212, off offset:1024
	v_cvt_pk_bf16_f32 v213, v12, v13
	s_mov_b64 s[0:1], 0xe000
	v_lshl_add_u64 v[220:221], v[228:229], 0, s[0:1]
	global_store_short v[220:221], v213, off
	global_store_short_d16_hi v[220:221], v213, off offset:1024
	v_cvt_pk_bf16_f32 v214, v14, v15
	s_mov_b64 s[0:1], 0xe800
	v_lshl_add_u64 v[222:223], v[228:229], 0, s[0:1]
	global_store_short v[222:223], v214, off
	global_store_short_d16_hi v[222:223], v214, off offset:1024
